# first k-iteration peeled also for the P7 GEMM (6 of 7 GEMM loops)
# baseline (speedup 1.0000x reference)
;     __device__ __forceinline__ bool next(int i, Unit& u) const { return decode(i * G + c, u); }
; #define PG8_STAGE(bufoff, gbase, voff) do { _Pragma("unroll") for (int _i = 0; _i < 2; ++_i) \
;         __builtin_amdgcn_global_load_lds((const unsigned*)((const char*)(gbase) + (voff)[_i]), (LAS unsigned*)(lds + (bufoff) + ldsw + _i * 8192), 16, 0, 0); } while (0)
; #define PG8_LDA(dst, b, h) do { _Pragma("unroll") for (int m = 0; m < 4; ++m) _Pragma("unroll") for (int k = 0; k < 2; ++k) dst[m][k] = *(const LAS bf16x8*)(lds + PG8_SA(b, h) + aoff + m * 2048 + k * 1024); } while (0)
; #define PG8_LDB(dst, b, h) do { _Pragma("unroll") for (int n = 0; n < 2; ++n) _Pragma("unroll") for (int k = 0; k < 2; ++k) dst[n][k] = *(const LAS bf16x8*)(lds + PG8_SB(b, h) + boff + n * 2048 + k * 1024); } while (0)
; #define PG8_WAIT_V(n) asm volatile("s_waitcnt vmcnt(" #n ")" ::: "memory")
; #define PG8_WAIT_L(n) asm volatile("s_waitcnt lgkmcnt(" #n ")" ::: "memory")
; #define PG8_BAR __builtin_amdgcn_s_barrier()
; #define PG8_SCHED __builtin_amdgcn_sched_barrier(0)
; template <class Epi, class Sched, bool DEFER>
; __device__ __forceinline__ void gemm_fast_core(LAS unsigned char* lds, const GemmP g, const Sched& S, const Epi& E, f32x4 (&acc)[2][2][4][2], Unit& cur) {
;     ...
;         const bool has_next = S.next(ui + 1, nxt);
;         const char* nA = has_next ? (const char*)g.aptr(nxt) : cA; const char* nB = has_next ? (const char*)g.bptr(nxt) : cB;
;         for (int t = 0; t < nt; t += 2) {
;             const bool last = (t == nt - 2);
;             const char* a1 = cA + (size_t)(t + 1) * kstep;
;             const char* a2 = last ? nA : cA + (size_t)(t + 2) * kstep; const char* b2 = last ? nB : cB + (size_t)(t + 2) * kstep;
;             const char* a3 = a2 + kstep; const char* b3 = b2 + kstep;
;             PG8_LDB(B0, 0, 0); PG8_LDB(B1, 0, 1); PG8_SCHED; PG8_LDA(At, 0, 0); PG8_STAGE(PG8_SA(1, 1), a1 + hstepA, voffA);
;             PG8_WAIT_V(8); PG8_WAIT_L(0); PG8_BAR; PG8_MMA(0, 0, At, B0); PG8_MMA(0, 1, At, B1); PG8_BAR; PG8_SCHED;
;             PG8_LDA(At, 0, 1); PG8_STAGE(PG8_SB(0, 0), b2, voffB); PG8_STAGE(PG8_SB(0, 1), b2 + hstepB, voffB); PG8_STAGE(PG8_SA(0, 0), a2, voffA);
;             PG8_WAIT_V(8); PG8_WAIT_L(0); PG8_BAR; PG8_MMA(1, 0, At, B0); PG8_MMA(1, 1, At, B1); PG8_BAR; PG8_SCHED;
.LBB0_1614:
	s_ashr_i32 s1, s0, 31
	s_lshl_b64 s[14:15], s[0:1], 20
	s_add_u32 s14, s90, s14
	s_addc_u32 s15, s91, s15
	s_and_b64 s[16:17], s[12:13], exec
	s_cselect_b32 s1, s15, s19
	s_cselect_b32 s35, s14, s18
	s_ashr_i32 s11, s10, 31
	s_lshl_b64 s[16:17], s[10:11], 20
	s_add_u32 s16, s72, s16
	s_addc_u32 s17, s73, s17
	s_and_b64 s[22:23], s[12:13], exec
	s_cselect_b32 s11, s17, s21
	s_cselect_b32 s36, s16, s20
	s_add_u32 s18, s18, 0x80080
	s_addc_u32 s19, s19, 0
	s_add_u32 s37, s20, 0x100
	s_addc_u32 s38, s21, 0
	s_mov_b32 s39, -2
	.p2align 6
	ds_read_b128 v[140:143], v137
	ds_read_b128 v[144:147], v137 offset:1024
	ds_read_b128 v[148:151], v137 offset:2048
	ds_read_b128 v[152:155], v137 offset:3072
	ds_read_b128 v[156:159], v138
	ds_read_b128 v[160:163], v138 offset:1024
	ds_read_b128 v[164:167], v138 offset:2048
	ds_read_b128 v[168:171], v138 offset:3072
	s_add_u32 s20, s18, 0xfff80080
	s_addc_u32 s21, s19, -1
	s_cmp_eq_u32 s39, 28
	s_cselect_b32 s23, s1, s21
	s_cselect_b32 s22, s35, s20
	s_cselect_b32 s21, s11, s38
	s_cselect_b32 s20, s36, s37
	v_lshl_add_u64 v[190:191], s[18:19], 0, v[132:133]
	s_add_i32 m0, s25, 0xc000
	ds_read_b128 v[172:175], v139
	ds_read_b128 v[176:179], v139 offset:1024
	ds_read_b128 v[180:183], v139 offset:2048
	ds_read_b128 v[184:187], v139 offset:3072
	ds_read_b128 v[192:195], v139 offset:4096
	ds_read_b128 v[196:199], v139 offset:5120
	ds_read_b128 v[200:203], v139 offset:6144
	ds_read_b128 v[204:207], v139 offset:7168
	global_load_lds_dwordx4 v[190:191], off
	v_lshl_add_u64 v[190:191], s[18:19], 0, v[134:135]
	s_add_i32 m0, s25, 0xe000
	s_nop 0
	global_load_lds_dwordx4 v[190:191], off
	s_waitcnt vmcnt(8)
	s_waitcnt lgkmcnt(0)
	s_barrier
	s_setprio 1
	s_waitcnt lgkmcnt(0)
	v_mfma_f32_16x16x32_bf16 v[128:131], v[140:143], v[172:175], 0
	v_mfma_f32_16x16x32_bf16 v[124:127], v[148:151], v[172:175], 0
	v_mfma_f32_16x16x32_bf16 v[112:115], v[140:143], v[180:183], 0
	v_mfma_f32_16x16x32_bf16 v[108:111], v[148:151], v[180:183], 0
	v_mfma_f32_16x16x32_bf16 v[96:99], v[140:143], v[192:195], 0
	v_mfma_f32_16x16x32_bf16 v[92:95], v[148:151], v[192:195], 0
	v_mfma_f32_16x16x32_bf16 v[80:83], v[140:143], v[200:203], 0
	v_mfma_f32_16x16x32_bf16 v[76:79], v[148:151], v[200:203], 0
	v_mfma_f32_16x16x32_bf16 v[128:131], v[144:147], v[176:179], v[128:131]
	v_mfma_f32_16x16x32_bf16 v[124:127], v[152:155], v[176:179], v[124:127]
	v_mfma_f32_16x16x32_bf16 v[112:115], v[144:147], v[184:187], v[112:115]
	v_mfma_f32_16x16x32_bf16 v[108:111], v[152:155], v[184:187], v[108:111]
	v_mfma_f32_16x16x32_bf16 v[96:99], v[144:147], v[196:199], v[96:99]
	v_mfma_f32_16x16x32_bf16 v[92:95], v[152:155], v[196:199], v[92:95]
	v_mfma_f32_16x16x32_bf16 v[80:83], v[144:147], v[204:207], v[80:83]
	v_mfma_f32_16x16x32_bf16 v[76:79], v[152:155], v[204:207], v[76:79]
	s_setprio 0
	s_setprio 1
	v_mfma_f32_16x16x32_bf16 v[120:123], v[156:159], v[172:175], 0
	v_mfma_f32_16x16x32_bf16 v[116:119], v[164:167], v[172:175], 0
	v_mfma_f32_16x16x32_bf16 v[104:107], v[156:159], v[180:183], 0
	v_mfma_f32_16x16x32_bf16 v[100:103], v[164:167], v[180:183], 0
	v_mfma_f32_16x16x32_bf16 v[88:91], v[156:159], v[192:195], 0
	v_mfma_f32_16x16x32_bf16 v[84:87], v[164:167], v[192:195], 0
	v_mfma_f32_16x16x32_bf16 v[72:75], v[156:159], v[200:203], 0
	v_mfma_f32_16x16x32_bf16 v[68:71], v[164:167], v[200:203], 0
	v_mfma_f32_16x16x32_bf16 v[120:123], v[160:163], v[176:179], v[120:123]
	v_mfma_f32_16x16x32_bf16 v[116:119], v[168:171], v[176:179], v[116:119]
	v_mfma_f32_16x16x32_bf16 v[104:107], v[160:163], v[184:187], v[104:107]
	v_mfma_f32_16x16x32_bf16 v[100:103], v[168:171], v[184:187], v[100:103]
	v_mfma_f32_16x16x32_bf16 v[88:91], v[160:163], v[196:199], v[88:91]
	v_mfma_f32_16x16x32_bf16 v[84:87], v[168:171], v[196:199], v[84:87]
	v_mfma_f32_16x16x32_bf16 v[72:75], v[160:163], v[204:207], v[72:75]
	v_mfma_f32_16x16x32_bf16 v[68:71], v[168:171], v[204:207], v[68:71]
	s_setprio 0
	s_barrier
	s_add_i32 s40, s33, s24
	v_lshl_add_u64 v[190:191], s[20:21], 0, v[0:1]
	s_mov_b32 m0, s40
	ds_read_b128 v[172:175], v139 offset:16384
	ds_read_b128 v[176:179], v139 offset:17408
	ds_read_b128 v[180:183], v139 offset:18432
	ds_read_b128 v[184:187], v139 offset:19456
	ds_read_b128 v[192:195], v139 offset:20480
	ds_read_b128 v[196:199], v139 offset:21504
	ds_read_b128 v[200:203], v139 offset:22528
	ds_read_b128 v[204:207], v139 offset:23552
	global_load_lds_dwordx4 v[190:191], off
	s_add_i32 m0, s40, 0x2000
	s_add_u32 s40, s20, 0x80000
	v_lshl_add_u64 v[208:209], s[20:21], 0, v[2:3]
	s_addc_u32 s41, s21, 0
	s_add_i32 s42, s34, s24
	global_load_lds_dwordx4 v[208:209], off
	v_lshl_add_u64 v[210:211], s[40:41], 0, v[0:1]
	s_mov_b32 m0, s42
	v_lshl_add_u64 v[212:213], s[22:23], 0, v[2:3]
	global_load_lds_dwordx4 v[210:211], off
	v_lshl_add_u64 v[210:211], s[40:41], 0, v[2:3]
	s_add_i32 m0, s42, 0x2000
	s_nop 0
	global_load_lds_dwordx4 v[210:211], off
	v_lshl_add_u64 v[210:211], s[22:23], 0, v[0:1]
	s_mov_b32 m0, s25
	s_nop 0
	global_load_lds_dwordx4 v[210:211], off
	s_mov_b32 m0, s26
	s_nop 0
	global_load_lds_dwordx4 v[212:213], off
	s_waitcnt vmcnt(8)
	s_waitcnt lgkmcnt(0)
	s_barrier
; #define PG8_STAGE(bufoff, gbase, voff) do { _Pragma("unroll") for (int _i = 0; _i < 2; ++_i) \
;         __builtin_amdgcn_global_load_lds((const unsigned*)((const char*)(gbase) + (voff)[_i]), (LAS unsigned*)(lds + (bufoff) + ldsw + _i * 8192), 16, 0, 0); } while (0)
; #define PG8_LDA(dst, b, h) do { _Pragma("unroll") for (int m = 0; m < 4; ++m) _Pragma("unroll") for (int k = 0; k < 2; ++k) dst[m][k] = *(const LAS bf16x8*)(lds + PG8_SA(b, h) + aoff + m * 2048 + k * 1024); } while (0)
; #define PG8_LDB(dst, b, h) do { _Pragma("unroll") for (int n = 0; n < 2; ++n) _Pragma("unroll") for (int k = 0; k < 2; ++k) dst[n][k] = *(const LAS bf16x8*)(lds + PG8_SB(b, h) + boff + n * 2048 + k * 1024); } while (0)
; #define PG8_MMA(ai, bj, At, Bt) do { __builtin_amdgcn_s_setprio(1); _Pragma("unroll") for (int m = 0; m < 4; ++m) _Pragma("unroll") for (int n = 0; n < 2; ++n) _Pragma("unroll") for (int k = 0; k < 2; ++k) \
;         acc[ai][bj][m][n] = __builtin_amdgcn_mfma_f32_16x16x32_bf16(Bt[n][k], At[m][k], acc[ai][bj][m][n], 0, 0, 0); __builtin_amdgcn_s_setprio(0); } while (0)
; #define PG8_WAIT_V(n) asm volatile("s_waitcnt vmcnt(" #n ")" ::: "memory")
; #define PG8_WAIT_L(n) asm volatile("s_waitcnt lgkmcnt(" #n ")" ::: "memory")
; #define PG8_BAR __builtin_amdgcn_s_barrier()
; #define PG8_SCHED __builtin_amdgcn_sched_barrier(0)
; template <class Epi, class Sched, bool DEFER>
; __device__ __forceinline__ void gemm_fast_core(LAS unsigned char* lds, const GemmP g, const Sched& S, const Epi& E, f32x4 (&acc)[2][2][4][2], Unit& cur) {
;     ...
;             PG8_WAIT_V(8); PG8_WAIT_L(0); PG8_BAR; PG8_MMA(1, 0, At, B0); PG8_MMA(1, 1, At, B1); PG8_BAR; PG8_SCHED;
;             PG8_LDB(B0, 1, 0); PG8_LDB(B1, 1, 1); PG8_SCHED; PG8_LDA(At, 1, 0); PG8_STAGE(PG8_SA(0, 1), a2 + hstepA, voffA);
;             PG8_WAIT_V(8); PG8_WAIT_L(0); PG8_BAR; PG8_MMA(0, 0, At, B0); PG8_MMA(0, 1, At, B1); PG8_BAR; PG8_SCHED;
;             PG8_LDA(At, 1, 1); PG8_STAGE(PG8_SB(1, 0), b3, voffB); PG8_STAGE(PG8_SB(1, 1), b3 + hstepB, voffB); PG8_STAGE(PG8_SA(1, 0), a3, voffA);
;             PG8_WAIT_V(8); PG8_WAIT_L(0); PG8_BAR; PG8_MMA(1, 0, At, B0); PG8_MMA(1, 1, At, B1); PG8_BAR; PG8_SCHED;
	s_setprio 1
	s_waitcnt lgkmcnt(0)
	v_mfma_f32_16x16x32_bf16 v[64:67], v[140:143], v[172:175], 0
	v_mfma_f32_16x16x32_bf16 v[60:63], v[148:151], v[172:175], 0
	v_mfma_f32_16x16x32_bf16 v[48:51], v[140:143], v[180:183], 0
	v_mfma_f32_16x16x32_bf16 v[44:47], v[148:151], v[180:183], 0
	v_mfma_f32_16x16x32_bf16 v[32:35], v[140:143], v[192:195], 0
	v_mfma_f32_16x16x32_bf16 v[28:31], v[148:151], v[192:195], 0
	v_mfma_f32_16x16x32_bf16 v[16:19], v[140:143], v[200:203], 0
	v_mfma_f32_16x16x32_bf16 v[12:15], v[148:151], v[200:203], 0
	v_mfma_f32_16x16x32_bf16 v[64:67], v[144:147], v[176:179], v[64:67]
	v_mfma_f32_16x16x32_bf16 v[60:63], v[152:155], v[176:179], v[60:63]
	v_mfma_f32_16x16x32_bf16 v[48:51], v[144:147], v[184:187], v[48:51]
	v_mfma_f32_16x16x32_bf16 v[44:47], v[152:155], v[184:187], v[44:47]
	v_mfma_f32_16x16x32_bf16 v[32:35], v[144:147], v[196:199], v[32:35]
	v_mfma_f32_16x16x32_bf16 v[28:31], v[152:155], v[196:199], v[28:31]
	v_mfma_f32_16x16x32_bf16 v[16:19], v[144:147], v[204:207], v[16:19]
	v_mfma_f32_16x16x32_bf16 v[12:15], v[152:155], v[204:207], v[12:15]
	s_setprio 0
	s_setprio 1
	v_mfma_f32_16x16x32_bf16 v[56:59], v[156:159], v[172:175], 0
	v_mfma_f32_16x16x32_bf16 v[52:55], v[164:167], v[172:175], 0
	v_mfma_f32_16x16x32_bf16 v[40:43], v[156:159], v[180:183], 0
	v_mfma_f32_16x16x32_bf16 v[36:39], v[164:167], v[180:183], 0
	v_mfma_f32_16x16x32_bf16 v[24:27], v[156:159], v[192:195], 0
	v_mfma_f32_16x16x32_bf16 v[20:23], v[164:167], v[192:195], 0
	v_mfma_f32_16x16x32_bf16 v[8:11], v[156:159], v[200:203], 0
	v_mfma_f32_16x16x32_bf16 v[4:7], v[164:167], v[200:203], 0
	v_mfma_f32_16x16x32_bf16 v[56:59], v[160:163], v[176:179], v[56:59]
	v_mfma_f32_16x16x32_bf16 v[52:55], v[168:171], v[176:179], v[52:55]
	v_mfma_f32_16x16x32_bf16 v[40:43], v[160:163], v[184:187], v[40:43]
	v_mfma_f32_16x16x32_bf16 v[36:39], v[168:171], v[184:187], v[36:39]
	v_mfma_f32_16x16x32_bf16 v[24:27], v[160:163], v[196:199], v[24:27]
	v_mfma_f32_16x16x32_bf16 v[20:23], v[168:171], v[196:199], v[20:23]
	v_mfma_f32_16x16x32_bf16 v[8:11], v[160:163], v[204:207], v[8:11]
	v_mfma_f32_16x16x32_bf16 v[4:7], v[168:171], v[204:207], v[4:7]
	s_setprio 0
	s_barrier
	s_add_i32 s40, 0, 0x18000
	s_add_i32 s41, 0, 0x1c000
	v_add_u32_e32 v152, s40, v136
	v_add_u32_e32 v168, s41, v136
	ds_read_b128 v[140:143], v152
	ds_read_b128 v[144:147], v152 offset:1024
	ds_read_b128 v[148:151], v152 offset:2048
	ds_read_b128 v[152:155], v152 offset:3072
	ds_read_b128 v[156:159], v168
	ds_read_b128 v[160:163], v168 offset:1024
	ds_read_b128 v[164:167], v168 offset:2048
	ds_read_b128 v[168:171], v168 offset:3072
	s_add_u32 s22, s22, 0x80000
	s_addc_u32 s23, s23, 0
	s_mov_b32 m0, s27
	v_lshl_add_u64 v[214:215], s[22:23], 0, v[0:1]
	ds_read_b128 v[172:175], v139 offset:32768
	ds_read_b128 v[176:179], v139 offset:33792
	ds_read_b128 v[180:183], v139 offset:34816
	ds_read_b128 v[184:187], v139 offset:35840
	ds_read_b128 v[192:195], v139 offset:36864
	ds_read_b128 v[196:199], v139 offset:37888
	ds_read_b128 v[200:203], v139 offset:38912
	ds_read_b128 v[204:207], v139 offset:39936
	global_load_lds_dwordx4 v[214:215], off
	v_lshl_add_u64 v[214:215], s[22:23], 0, v[2:3]
	s_mov_b32 m0, s28
	s_nop 0
	global_load_lds_dwordx4 v[214:215], off
	s_waitcnt vmcnt(8)
	s_waitcnt lgkmcnt(0)
	s_barrier
	s_setprio 1
	s_waitcnt lgkmcnt(0)
	v_mfma_f32_16x16x32_bf16 v[128:131], v[140:143], v[172:175], v[128:131]
	v_mfma_f32_16x16x32_bf16 v[124:127], v[148:151], v[172:175], v[124:127]
	v_mfma_f32_16x16x32_bf16 v[112:115], v[140:143], v[180:183], v[112:115]
	v_mfma_f32_16x16x32_bf16 v[108:111], v[148:151], v[180:183], v[108:111]
	v_mfma_f32_16x16x32_bf16 v[96:99], v[140:143], v[192:195], v[96:99]
	v_mfma_f32_16x16x32_bf16 v[92:95], v[148:151], v[192:195], v[92:95]
	v_mfma_f32_16x16x32_bf16 v[80:83], v[140:143], v[200:203], v[80:83]
	v_mfma_f32_16x16x32_bf16 v[76:79], v[148:151], v[200:203], v[76:79]
	v_mfma_f32_16x16x32_bf16 v[128:131], v[144:147], v[176:179], v[128:131]
	v_mfma_f32_16x16x32_bf16 v[124:127], v[152:155], v[176:179], v[124:127]
	v_mfma_f32_16x16x32_bf16 v[112:115], v[144:147], v[184:187], v[112:115]
	v_mfma_f32_16x16x32_bf16 v[108:111], v[152:155], v[184:187], v[108:111]
	v_mfma_f32_16x16x32_bf16 v[96:99], v[144:147], v[196:199], v[96:99]
	v_mfma_f32_16x16x32_bf16 v[92:95], v[152:155], v[196:199], v[92:95]
	v_mfma_f32_16x16x32_bf16 v[80:83], v[144:147], v[204:207], v[80:83]
	v_mfma_f32_16x16x32_bf16 v[76:79], v[152:155], v[204:207], v[76:79]
	s_setprio 0
	s_setprio 1
	v_mfma_f32_16x16x32_bf16 v[120:123], v[156:159], v[172:175], v[120:123]
	v_mfma_f32_16x16x32_bf16 v[116:119], v[164:167], v[172:175], v[116:119]
	v_mfma_f32_16x16x32_bf16 v[104:107], v[156:159], v[180:183], v[104:107]
	v_mfma_f32_16x16x32_bf16 v[100:103], v[164:167], v[180:183], v[100:103]
	v_mfma_f32_16x16x32_bf16 v[88:91], v[156:159], v[192:195], v[88:91]
	v_mfma_f32_16x16x32_bf16 v[84:87], v[164:167], v[192:195], v[84:87]
	v_mfma_f32_16x16x32_bf16 v[72:75], v[156:159], v[200:203], v[72:75]
	v_mfma_f32_16x16x32_bf16 v[68:71], v[164:167], v[200:203], v[68:71]
	v_mfma_f32_16x16x32_bf16 v[120:123], v[160:163], v[176:179], v[120:123]
	v_mfma_f32_16x16x32_bf16 v[116:119], v[168:171], v[176:179], v[116:119]
	v_mfma_f32_16x16x32_bf16 v[104:107], v[160:163], v[184:187], v[104:107]
	v_mfma_f32_16x16x32_bf16 v[100:103], v[168:171], v[184:187], v[100:103]
	v_mfma_f32_16x16x32_bf16 v[88:91], v[160:163], v[196:199], v[88:91]
	v_mfma_f32_16x16x32_bf16 v[84:87], v[168:171], v[196:199], v[84:87]
	v_mfma_f32_16x16x32_bf16 v[72:75], v[160:163], v[204:207], v[72:75]
	v_mfma_f32_16x16x32_bf16 v[68:71], v[168:171], v[204:207], v[68:71]
	s_setprio 0
	s_barrier
; #define PG8_STAGE(bufoff, gbase, voff) do { _Pragma("unroll") for (int _i = 0; _i < 2; ++_i) \
;         __builtin_amdgcn_global_load_lds((const unsigned*)((const char*)(gbase) + (voff)[_i]), (LAS unsigned*)(lds + (bufoff) + ldsw + _i * 8192), 16, 0, 0); } while (0)
; #define PG8_LDA(dst, b, h) do { _Pragma("unroll") for (int m = 0; m < 4; ++m) _Pragma("unroll") for (int k = 0; k < 2; ++k) dst[m][k] = *(const LAS bf16x8*)(lds + PG8_SA(b, h) + aoff + m * 2048 + k * 1024); } while (0)
; #define PG8_MMA(ai, bj, At, Bt) do { __builtin_amdgcn_s_setprio(1); _Pragma("unroll") for (int m = 0; m < 4; ++m) _Pragma("unroll") for (int n = 0; n < 2; ++n) _Pragma("unroll") for (int k = 0; k < 2; ++k) \
;         acc[ai][bj][m][n] = __builtin_amdgcn_mfma_f32_16x16x32_bf16(Bt[n][k], At[m][k], acc[ai][bj][m][n], 0, 0, 0); __builtin_amdgcn_s_setprio(0); } while (0)
; #define PG8_WAIT_V(n) asm volatile("s_waitcnt vmcnt(" #n ")" ::: "memory")
; #define PG8_WAIT_L(n) asm volatile("s_waitcnt lgkmcnt(" #n ")" ::: "memory")
; #define PG8_BAR __builtin_amdgcn_s_barrier()
; #define PG8_SCHED __builtin_amdgcn_sched_barrier(0)
; template <class Epi, class Sched, bool DEFER>
; __device__ __forceinline__ void gemm_fast_core(LAS unsigned char* lds, const GemmP g, const Sched& S, const Epi& E, f32x4 (&acc)[2][2][4][2], Unit& cur) {
;     ...
;         for (int t = 0; t < nt; t += 2) {
;     ...
;             PG8_LDA(At, 1, 1); PG8_STAGE(PG8_SB(1, 0), b3, voffB); PG8_STAGE(PG8_SB(1, 1), b3 + hstepB, voffB); PG8_STAGE(PG8_SA(1, 0), a3, voffA);
;             PG8_WAIT_V(8); PG8_WAIT_L(0); PG8_BAR; PG8_MMA(1, 0, At, B0); PG8_MMA(1, 1, At, B1); PG8_BAR; PG8_SCHED;
	s_add_i32 s22, s40, s24
	v_lshl_add_u64 v[190:191], v[190:191], 0, s[6:7]
	s_mov_b32 m0, s22
	ds_read_b128 v[172:175], v139 offset:49152
	ds_read_b128 v[176:179], v139 offset:50176
	ds_read_b128 v[180:183], v139 offset:51200
	ds_read_b128 v[184:187], v139 offset:52224
	ds_read_b128 v[192:195], v139 offset:53248
	ds_read_b128 v[196:199], v139 offset:54272
	ds_read_b128 v[200:203], v139 offset:55296
	ds_read_b128 v[204:207], v139 offset:56320
	global_load_lds_dwordx4 v[190:191], off
	s_add_i32 m0, s22, 0x2000
	s_add_u32 s20, s20, 0x80080
	v_lshl_add_u64 v[190:191], v[208:209], 0, s[6:7]
	s_addc_u32 s21, s21, 0
	s_add_i32 s22, s41, s24
	global_load_lds_dwordx4 v[190:191], off
	v_lshl_add_u64 v[190:191], s[20:21], 0, v[0:1]
	s_mov_b32 m0, s22
	s_nop 0
	global_load_lds_dwordx4 v[190:191], off
	v_lshl_add_u64 v[190:191], s[20:21], 0, v[2:3]
	s_add_i32 m0, s22, 0x2000
	s_nop 0
	global_load_lds_dwordx4 v[190:191], off
	v_lshl_add_u64 v[190:191], v[210:211], 0, s[6:7]
	s_mov_b32 m0, s30
	s_nop 0
	global_load_lds_dwordx4 v[190:191], off
	v_lshl_add_u64 v[190:191], v[212:213], 0, s[6:7]
	s_mov_b32 m0, s31
	s_nop 0
	global_load_lds_dwordx4 v[190:191], off
	s_waitcnt vmcnt(8)
	s_waitcnt lgkmcnt(0)
	s_barrier
	s_setprio 1
	s_waitcnt lgkmcnt(0)
	v_mfma_f32_16x16x32_bf16 v[64:67], v[140:143], v[172:175], v[64:67]
	v_mfma_f32_16x16x32_bf16 v[60:63], v[148:151], v[172:175], v[60:63]
	v_mfma_f32_16x16x32_bf16 v[48:51], v[140:143], v[180:183], v[48:51]
	v_mfma_f32_16x16x32_bf16 v[44:47], v[148:151], v[180:183], v[44:47]
	v_mfma_f32_16x16x32_bf16 v[32:35], v[140:143], v[192:195], v[32:35]
	v_mfma_f32_16x16x32_bf16 v[28:31], v[148:151], v[192:195], v[28:31]
	v_mfma_f32_16x16x32_bf16 v[16:19], v[140:143], v[200:203], v[16:19]
	v_mfma_f32_16x16x32_bf16 v[12:15], v[148:151], v[200:203], v[12:15]
	v_mfma_f32_16x16x32_bf16 v[64:67], v[144:147], v[176:179], v[64:67]
	v_mfma_f32_16x16x32_bf16 v[60:63], v[152:155], v[176:179], v[60:63]
	v_mfma_f32_16x16x32_bf16 v[48:51], v[144:147], v[184:187], v[48:51]
	v_mfma_f32_16x16x32_bf16 v[44:47], v[152:155], v[184:187], v[44:47]
	v_mfma_f32_16x16x32_bf16 v[32:35], v[144:147], v[196:199], v[32:35]
	v_mfma_f32_16x16x32_bf16 v[28:31], v[152:155], v[196:199], v[28:31]
	v_mfma_f32_16x16x32_bf16 v[16:19], v[144:147], v[204:207], v[16:19]
	v_mfma_f32_16x16x32_bf16 v[12:15], v[152:155], v[204:207], v[12:15]
	s_setprio 0
	s_setprio 1
	v_mfma_f32_16x16x32_bf16 v[56:59], v[156:159], v[172:175], v[56:59]
	v_mfma_f32_16x16x32_bf16 v[52:55], v[164:167], v[172:175], v[52:55]
	v_mfma_f32_16x16x32_bf16 v[40:43], v[156:159], v[180:183], v[40:43]
	v_mfma_f32_16x16x32_bf16 v[36:39], v[164:167], v[180:183], v[36:39]
	v_mfma_f32_16x16x32_bf16 v[24:27], v[156:159], v[192:195], v[24:27]
	v_mfma_f32_16x16x32_bf16 v[20:23], v[164:167], v[192:195], v[20:23]
	v_mfma_f32_16x16x32_bf16 v[8:11], v[156:159], v[200:203], v[8:11]
	v_mfma_f32_16x16x32_bf16 v[4:7], v[164:167], v[200:203], v[4:7]
	v_mfma_f32_16x16x32_bf16 v[56:59], v[160:163], v[176:179], v[56:59]
	v_mfma_f32_16x16x32_bf16 v[52:55], v[168:171], v[176:179], v[52:55]
	v_mfma_f32_16x16x32_bf16 v[40:43], v[160:163], v[184:187], v[40:43]
	v_mfma_f32_16x16x32_bf16 v[36:39], v[168:171], v[184:187], v[36:39]
	v_mfma_f32_16x16x32_bf16 v[24:27], v[160:163], v[196:199], v[24:27]
	v_mfma_f32_16x16x32_bf16 v[20:23], v[168:171], v[196:199], v[20:23]
	v_mfma_f32_16x16x32_bf16 v[8:11], v[160:163], v[204:207], v[8:11]
	v_mfma_f32_16x16x32_bf16 v[4:7], v[168:171], v[204:207], v[4:7]
	s_setprio 0
	s_barrier
	s_add_i32 s39, s39, 2
	s_add_u32 s18, s18, 0x100
	s_addc_u32 s19, s19, 0
	s_add_u32 s37, s37, 0x100
	s_addc_u32 s38, s38, 0
	s_cmp_gt_u32 s39, 29
	s_cbranch_scc0 .LBB0_1615
	s_branch .Lpeel_p7_done
	.p2align 6

; #define PG8_BAR __builtin_amdgcn_s_barrier()
; template <class Epi, class Sched, bool DEFER>
; __device__ __forceinline__ void gemm_fast_core(LAS unsigned char* lds, const GemmP g, const Sched& S, const Epi& E, f32x4 (&acc)[2][2][4][2], Unit& cur) {
;     ...
;         if (wr == 0) PG8_BAR;
;         if constexpr (DEFER) {   }
;         else if constexpr (Epi::TILE) E.tile(acc, cur, wr, wc, fr, fq);
;         else {
;             const int row0 = cur.pm * BM + wr * 64 + fr, col0 = cur.pn * BM + wc * 32 + 4 * fq;
; #pragma unroll
;             for (int ai = 0; ai < 2; ++ai)
; #pragma unroll
;                 for (int m = 0; m < 4; ++m)
; #pragma unroll
;                     for (int bj = 0; bj < 2; ++bj)
; #pragma unroll
;                         for (int n = 0; n < 2; ++n) E.put(cur, row0 + ai * HALF + m * 16, col0 + bj * HALF + n * 16, acc[ai][bj][m][n]);
;         }
;         if (!has_next) break;
; #pragma unroll
;         for (int a = 0; a < 2; ++a)
; #pragma unroll
;             for (int b = 0; b < 2; ++b)
; #pragma unroll
;                 for (int m = 0; m < 4; ++m)
; #pragma unroll
;                     for (int n = 0; n < 2; ++n) acc[a][b][m][n] = (f32x4){0.f, 0.f, 0.f, 0.f};
;         cur = nxt; cA = nA; cB = nB; ++ui;
;         if (wr == 1) PG8_BAR;
.Lpeel_p7_done:
	s_and_b64 vcc, exec, s[8:9]
	s_cbranch_vccz .LBB0_1618
	s_barrier
	s_andn2_b64 vcc, exec, s[12:13]
	s_mov_b64 s[12:13], -1
	s_cbranch_vccnz .LBB0_1607
	s_branch .LBB0_1619
